# softmax row sums with v_pk_add_f32 (15 packed f32 adds replace 32 scalar adds per KV tile); same f32 even/odd accumulation
# speedup vs baseline: 1.0000x; 1.0000x over previous
.LBB0_381:
	s_barrier
	s_mulk_i32 s3, 0x2400
	v_add3_u32 v190, v143, s3, v142
	v_add_u32_e32 v191, 0x6800, v190
	v_add_u32_e32 v192, 0x7a00, v190
	ds_read2_b64 v[194:197], v191 offset1:2
	ds_read2_b64 v[198:201], v192 offset1:2
	ds_read2_b64 v[202:205], v191 offset0:4 offset1:6
	ds_read2_b64 v[206:209], v192 offset0:4 offset1:6
	ds_read2_b64 v[210:213], v191 offset0:8 offset1:10
	ds_read2_b64 v[214:217], v192 offset0:8 offset1:10
	ds_read2_b64 v[218:221], v191 offset0:12 offset1:14
	ds_read2_b64 v[222:225], v192 offset0:12 offset1:14
	v_exp_f32_e32 v32, v32
	v_exp_f32_e32 v33, v33
	v_exp_f32_e32 v34, v34
	v_exp_f32_e32 v35, v35
	v_exp_f32_e32 v36, v36
	v_exp_f32_e32 v37, v37
	v_exp_f32_e32 v38, v38
	v_exp_f32_e32 v39, v39
	v_cvt_pk_bf16_f32 v160, v32, v33
	v_cvt_pk_bf16_f32 v161, v34, v35
	v_cvt_pk_bf16_f32 v162, v36, v37
	v_cvt_pk_bf16_f32 v163, v38, v39
	v_pk_add_f32 v[168:169], v[32:33], v[34:35]
	v_pk_add_f32 v[168:169], v[168:169], v[36:37]
	v_pk_add_f32 v[168:169], v[168:169], v[38:39]
	s_waitcnt lgkmcnt(6)
	v_mfma_f32_32x32x16_bf16 v[16:31], v[194:197], v[160:163], v[16:31]
	v_mfma_f32_32x32x16_bf16 v[0:15], v[198:201], v[160:163], v[0:15]
	v_exp_f32_e32 v40, v40
	v_exp_f32_e32 v41, v41
	v_exp_f32_e32 v42, v42
	v_exp_f32_e32 v43, v43
	v_exp_f32_e32 v44, v44
	v_exp_f32_e32 v45, v45
	v_exp_f32_e32 v46, v46
	v_exp_f32_e32 v47, v47
	v_cvt_pk_bf16_f32 v164, v40, v41
	v_cvt_pk_bf16_f32 v165, v42, v43
	v_cvt_pk_bf16_f32 v166, v44, v45
	v_cvt_pk_bf16_f32 v167, v46, v47
	v_pk_add_f32 v[168:169], v[168:169], v[40:41]
	v_pk_add_f32 v[168:169], v[168:169], v[42:43]
	v_pk_add_f32 v[168:169], v[168:169], v[44:45]
	v_pk_add_f32 v[168:169], v[168:169], v[46:47]
	s_waitcnt lgkmcnt(4)
	v_mfma_f32_32x32x16_bf16 v[16:31], v[202:205], v[164:167], v[16:31]
	v_mfma_f32_32x32x16_bf16 v[0:15], v[206:209], v[164:167], v[0:15]
	v_exp_f32_e32 v48, v48
	v_exp_f32_e32 v49, v49
	v_exp_f32_e32 v50, v50
	v_exp_f32_e32 v51, v51
	v_exp_f32_e32 v52, v52
	v_exp_f32_e32 v53, v53
	v_exp_f32_e32 v54, v54
	v_exp_f32_e32 v55, v55
	v_cvt_pk_bf16_f32 v160, v48, v49
	v_cvt_pk_bf16_f32 v161, v50, v51
	v_cvt_pk_bf16_f32 v162, v52, v53
	v_cvt_pk_bf16_f32 v163, v54, v55
	v_pk_add_f32 v[168:169], v[168:169], v[48:49]
	v_pk_add_f32 v[168:169], v[168:169], v[50:51]
	v_pk_add_f32 v[168:169], v[168:169], v[52:53]
	v_pk_add_f32 v[168:169], v[168:169], v[54:55]
	s_waitcnt lgkmcnt(2)
	v_mfma_f32_32x32x16_bf16 v[16:31], v[210:213], v[160:163], v[16:31]
	v_mfma_f32_32x32x16_bf16 v[0:15], v[214:217], v[160:163], v[0:15]
	v_exp_f32_e32 v56, v56
	v_exp_f32_e32 v57, v57
	v_exp_f32_e32 v58, v58
	v_exp_f32_e32 v59, v59
	v_exp_f32_e32 v60, v60
	v_exp_f32_e32 v61, v61
	v_exp_f32_e32 v62, v62
	v_exp_f32_e32 v63, v63
	v_cvt_pk_bf16_f32 v164, v56, v57
	v_cvt_pk_bf16_f32 v165, v58, v59
	v_cvt_pk_bf16_f32 v166, v60, v61
	v_cvt_pk_bf16_f32 v167, v62, v63
	v_pk_add_f32 v[168:169], v[168:169], v[56:57]
	v_pk_add_f32 v[168:169], v[168:169], v[58:59]
	v_pk_add_f32 v[168:169], v[168:169], v[60:61]
	v_pk_add_f32 v[168:169], v[168:169], v[62:63]
	v_add_f32_e32 v168, v168, v169
	v_add_f32_e32 v119, v119, v168
	s_add_i32 s1, s1, 64
	s_cmpk_lg_i32 s1, 0x11c0
	s_waitcnt lgkmcnt(0)
	s_barrier
	v_mfma_f32_32x32x16_bf16 v[16:31], v[218:221], v[164:167], v[16:31]
	v_mfma_f32_32x32x16_bf16 v[0:15], v[222:225], v[164:167], v[0:15]
	s_cbranch_scc0 .LBB0_383
	s_mov_b32 s3, s2
	s_branch .LBB0_377
